# summary pass tile loop: next-tile weight/bias load addressing simplified (loop-invariant 64-bit adds hoisted, bias loads through SGPR base + 32-bit index): 23 fewer VALU per tile
# speedup vs baseline: 1.0071x; 1.0011x over previous
.LBB0_391:
	v_readlane_b32 s4, v252, 0
	v_readlane_b32 s5, v252, 1
	s_waitcnt lgkmcnt(0)
	s_barrier
	s_load_dwordx4 s[44:47], s[4:5], 0x40
	s_nop 0
	s_load_dwordx2 s[4:5], s[4:5], 0xc8
	v_readlane_b32 s6, v252, 4
	v_mbcnt_lo_u32_b32 v0, -1, 0
	v_mbcnt_hi_u32_b32 v0, -1, v0
	v_readlane_b32 s28, v253, 41
	v_readlane_b32 s29, v253, 42
	s_waitcnt lgkmcnt(0)
	s_add_u32 s24, s4, 0x200000
	s_addc_u32 s25, s5, 0
	s_add_u32 s26, s4, 0x4200000
	s_addc_u32 s27, s5, 0
	s_add_u32 s33, s4, 0xf600000
	s_addc_u32 s36, s5, 0
	s_add_u32 s22, s4, 0x180000
	v_or_b32_e32 v180, s6, v0
	s_addc_u32 s23, s5, 0
	s_add_u32 s6, s4, 0x188000
	v_and_b32_e32 v181, 63, v180
	v_ashrrev_i32_e32 v0, 6, v180
	v_and_b32_e32 v185, 15, v180
	v_and_b32_e32 v1, 3, v180
	v_lshlrev_b32_e32 v2, 2, v180
	v_readfirstlane_b32 s37, v0
	s_addc_u32 s7, s5, 0
	s_andn2_b64 vcc, exec, s[28:29]
	v_and_b32_e32 v183, 48, v180
	v_cmp_gt_u32_e64 s[40:41], 16, v181
	v_and_or_b32 v184, v2, 48, v1
	v_lshlrev_b32_e32 v182, 2, v185
	s_cbranch_vccnz .LBB0_432
	s_lshl_b32 s28, s56, 5
	s_add_i32 s28, s37, s28
	v_and_b32_e32 v148, 48, v181
	s_lshl_b32 s34, s56, 2
	s_ashr_i32 s29, s28, 31
	v_lshl_add_u64 v[2:3], s[24:25], 0, v[148:149]
	s_lshl_b64 s[28:29], s[28:29], 13
	s_or_b32 s34, s34, 1
	v_lshl_add_u64 v[4:5], v[2:3], 0, s[28:29]
	s_lshl_b32 s28, s34, 3
	s_add_i32 s28, s37, s28
	s_ashr_i32 s29, s28, 31
	s_lshl_b32 s30, s37, 6
	v_lshlrev_b32_e32 v148, 7, v185
	s_lshl_b64 s[28:29], s[28:29], 13
	v_or_b32_e32 v186, s30, v185
	v_lshl_add_u64 v[132:133], v[4:5], 0, v[148:149]
	v_lshl_add_u64 v[4:5], v[2:3], 0, s[28:29]
	s_lshl_b32 s96, s56, 11
	s_lshl_b32 s31, s56, 1
	v_lshl_add_u64 v[134:135], v[4:5], 0, v[148:149]
	v_add_u32_e32 v4, s96, v186
	v_ashrrev_i32_e32 v5, 31, v4
	s_lshl_b32 s28, s56, 10
	s_or_b32 s31, s31, 1
	v_lshl_add_u64 v[136:137], v[4:5], 2, s[22:23]
	v_subrev_u32_e32 v4, s28, v4
	s_lshl_b32 s28, s31, 4
	s_add_i32 s28, s37, s28
	v_lshl_add_u32 v6, s34, 9, v186
	s_lshl_b32 s34, s31, 1
	s_ashr_i32 s29, s28, 31
	v_ashrrev_i32_e32 v5, 31, v4
	s_lshl_b64 s[28:29], s[28:29], 13
	s_or_b32 s34, s34, 1
	v_lshl_add_u64 v[140:141], v[4:5], 2, s[6:7]
	v_lshl_add_u64 v[4:5], v[2:3], 0, s[28:29]
	s_lshl_b32 s28, s34, 3
	s_add_i32 s28, s37, s28
	s_ashr_i32 s29, s28, 31
	s_lshl_b64 s[28:29], s[28:29], 13
	v_lshl_add_u64 v[2:3], v[2:3], 0, s[28:29]
	v_lshl_add_u64 v[144:145], v[2:3], 0, v[148:149]
	v_lshl_add_u32 v2, s31, 10, v186
	v_ashrrev_i32_e32 v3, 31, v2
	s_lshl_b32 s28, s31, 9
	v_lshl_add_u64 v[146:147], v[2:3], 2, s[22:23]
	v_subrev_u32_e32 v2, s28, v2
	v_lshl_add_u64 v[142:143], v[4:5], 0, v[148:149]
	v_lshl_add_u32 v4, s34, 9, v186
	v_ashrrev_i32_e32 v3, 31, v2
	v_ashrrev_i32_e32 v5, 31, v4
	v_lshl_add_u64 v[158:159], v[2:3], 2, s[6:7]
	v_lshlrev_b32_e32 v2, 5, v181
	v_mov_b32_e32 v3, v149
	v_lshl_add_u64 v[156:157], v[4:5], 2, s[22:23]
	v_lshl_add_u64 v[4:5], s[44:45], 0, v[2:3]
	v_lshl_add_u64 v[160:161], s[96:97], 2, v[4:5]
	s_lshl_b32 s96, s56, 9
	s_lshl_b64 s[28:29], s[96:97], 2
	s_add_u32 s28, s46, s28
	s_addc_u32 s29, s47, s29
	v_lshl_add_u64 v[166:167], s[28:29], 0, v[2:3]
	s_movk_i32 s28, 0x2080
	v_mul_lo_u32 v5, v0, s28
	s_lshl_b32 s28, s37, 7
	v_ashrrev_i32_e32 v7, 31, v6
	s_add_i32 s28, s28, 0
	v_lshrrev_b32_e32 v1, 4, v181
	v_lshl_add_u64 v[138:139], v[6:7], 2, s[22:23]
	v_add_u32_e32 v6, s28, v183
	s_movk_i32 s28, 0x4100
	v_mad_u32_u24 v189, v1, s28, 0
	v_readlane_b32 s28, v254, 33
	s_add_i32 s28, s37, s28
	s_ashr_i32 s29, s28, 31
	s_lshl_b64 s[28:29], s[28:29], 13
	v_lshlrev_b32_e32 v187, 3, v0
	v_or3_b32 v0, s28, v148, v183
	v_readlane_b32 s28, v254, 20
	s_add_i32 s28, s37, s28
	v_mov_b32_e32 v1, s29
	s_ashr_i32 s29, s28, 31
	s_lshl_b64 s[28:29], s[28:29], 13
	v_lshl_add_u64 v[170:171], s[4:5], 0, v[0:1]
	v_or3_b32 v0, s28, v148, v183
	v_readlane_b32 s28, v252, 62
	s_add_i32 s28, s37, s28
	v_mov_b32_e32 v1, s29
	s_ashr_i32 s29, s28, 31
	s_lshl_b64 s[28:29], s[28:29], 13
	v_lshl_add_u64 v[172:173], s[4:5], 0, v[0:1]
	v_or3_b32 v0, s28, v148, v183
	v_readlane_b32 s28, v254, 42
	s_add_i32 s28, s37, s28
	v_mov_b32_e32 v1, s29
	s_ashr_i32 s29, s28, 31
	s_lshl_b64 s[28:29], s[28:29], 13
	v_lshl_add_u64 v[174:175], s[4:5], 0, v[0:1]
	v_or3_b32 v0, s28, v148, v183
	v_readlane_b32 s28, v254, 41
	s_add_i32 s28, s28, s30
	s_mul_i32 s34, s37, 0x7000
	v_add_u32_e32 v193, s28, v185
	v_readlane_b32 s28, v254, 40
	s_add_i32 s28, s28, s30
	s_mul_hi_i32 s31, s37, 0x7000
	v_add_u32_e32 v194, s28, v185
	s_add_u32 s28, s4, s34
	v_lshlrev_b32_e32 v2, 4, v181
	v_mov_b32_e32 v1, s29
	s_addc_u32 s29, s5, s31
	v_add_u32_e32 v4, 0, v2
	v_mul_u32_u24_e32 v7, 0x410, v184
	v_lshl_add_u64 v[176:177], s[4:5], 0, v[0:1]
	v_add_co_u32_e32 v242, vcc, s2, v176
	s_nop 1
	v_addc_co_u32_e32 v243, vcc, 0, v177, vcc
	v_add_co_u32_e32 v244, vcc, s2, v174
	s_nop 1
	v_addc_co_u32_e32 v245, vcc, 0, v175, vcc
	v_add_co_u32_e32 v246, vcc, s2, v172
	s_nop 1
	v_addc_co_u32_e32 v247, vcc, 0, v173, vcc
	v_add_co_u32_e32 v248, vcc, s2, v170
	s_nop 1
	v_addc_co_u32_e32 v249, vcc, 0, v171, vcc
	v_lshl_add_u64 v[0:1], s[28:29], 0, v[2:3]
	s_mov_b64 s[28:29], 0xb700000
	v_lshl_add_u64 v[162:163], v[160:161], 0, s[14:15]
	v_lshl_add_u64 v[164:165], v[160:161], 0, s[16:17]
	v_lshl_add_u64 v[168:169], s[26:27], 0, v[2:3]
	v_add_u32_e32 v188, -2, v187
	v_or_b32_e32 v190, 64, v182
	v_or_b32_e32 v191, 0x80, v182
	v_or_b32_e32 v192, 0xc0, v182
	v_lshl_add_u64 v[178:179], v[0:1], 0, s[28:29]
	v_add_u32_e32 v195, v4, v5
	v_add_u32_e32 v196, v6, v7
	s_mov_b32 s38, s95
	s_branch .LBB0_394

.LBB0_426:
	s_mov_b32 s34, 48
	s_cmpk_eq_i32 s30, 0x1800
	v_mov_b32_e32 v197, v104
	v_mov_b32_e32 v200, v16
	v_mov_b32_e32 v198, v96
	v_mov_b32_e32 v201, v4
	v_mov_b32_e32 v199, v6
	v_mov_b32_e32 v202, v148
	s_cbranch_scc1 .LBB0_428
	v_lshl_add_u64 v[18:19], v[242:243], 0, s[30:31]
	v_lshl_add_u64 v[68:69], v[244:245], 0, s[30:31]
	v_add_u32_e32 v5, s39, v193
	global_load_dwordx4 v[56:59], v[18:19], off offset:2048
	global_load_dwordx4 v[60:63], v[68:69], off offset:2048
	global_load_dwordx4 v[64:67], v[18:19], off offset:2112
	s_nop 0
	global_load_dwordx4 v[68:71], v[68:69], off offset:2112
	v_lshlrev_b32_e32 v18, 2, v5
	v_add_u32_e32 v7, s39, v194
	global_load_dword v197, v18, s[22:23] offset:64
	global_load_dword v198, v18, s[22:23] offset:2112
	v_lshlrev_b32_e32 v7, 2, v7
	global_load_dword v199, v7, s[6:7] offset:64
	v_lshl_add_u64 v[76:77], v[246:247], 0, s[30:31]
	v_lshl_add_u64 v[84:85], v[248:249], 0, s[30:31]
	v_add_u32_e32 v18, 0x1000, v18
	global_load_dwordx4 v[72:75], v[76:77], off offset:2048
	global_load_dwordx4 v[80:83], v[84:85], off offset:2048
	s_nop 0
	global_load_dwordx4 v[76:79], v[76:77], off offset:2112
	s_nop 0
	global_load_dwordx4 v[84:87], v[84:85], off offset:2112
	global_load_dword v200, v18, s[22:23] offset:64
	global_load_dword v201, v18, s[22:23] offset:2112
	global_load_dword v202, v7, s[6:7] offset:2112
	s_mov_b32 s34, s39
